# no store drain at EVENA/EVENB unit-end barriers (on top of SCAN, GEMV pipelines, ATTN DPP reduction)
# speedup vs baseline: 1.0029x; 1.0029x over previous
.LBB0_464:
	s_and_b32 s5, s4, 3
	s_and_b32 s13, s12, 0xfc0
	s_and_b32 s14, s12, 0xffffffc0
	v_mov_b64_e32 v[0:1], s[6:7]
	s_getpc_b64 s[10:11]
	s_add_u32 s10, s10, _ZN2mk5LOG2GE@rel32@lo+4
	s_addc_u32 s11, s11, _ZN2mk5LOG2GE@rel32@hi+12
	s_movk_i32 s15, 0xf000
	v_add_u32_e32 v3, s14, v38
	s_lshl_b32 s26, s5, 8
	v_add_u32_e32 v2, s13, v38
	v_add_co_u32_e32 v36, vcc, s15, v34
	v_mad_i64_i32 v[0:1], s[14:15], v3, s85, v[0:1]
	v_ashrrev_i32_e32 v3, 31, v2
	v_lshl_add_u64 v[0:1], v[0:1], 0, s[26:27]
	v_addc_co_u32_e32 v37, vcc, -1, v35, vcc
	v_lshlrev_b64 v[2:3], 9, v[2:3]
	v_lshl_add_u64 v[16:17], v[0:1], 0, v[168:169]
	s_lshl_b32 s5, s5, 2
	v_lshl_add_u64 v[12:13], v[32:33], 0, v[2:3]
	v_add_co_u32_e32 v28, vcc, 0x1000, v16
	s_load_dword s5, s[10:11], s5 offset:0x0
	global_load_dwordx4 v[0:3], v[12:13], off
	global_load_dwordx4 v[4:7], v[12:13], off offset:16
	global_load_dwordx4 v[8:11], v[12:13], off offset:48
	s_nop 0
	global_load_dwordx4 v[12:15], v[12:13], off offset:32
	v_addc_co_u32_e32 v29, vcc, 0, v17, vcc
	global_load_dwordx4 v[16:19], v[28:29], off
	global_load_dwordx4 v[20:23], v[28:29], off offset:128
	global_load_dwordx4 v[24:27], v[28:29], off offset:1024
	s_nop 0
	global_load_dwordx4 v[28:31], v[28:29], off offset:1152
	s_waitcnt lgkmcnt(0)
	v_mul_f32_e32 v44, s5, v39
	v_exp_f32_e32 v44, v44
	s_add_i32 s4, s4, s24
	s_add_i32 s12, s12, s76
	s_cmpk_lt_i32 s4, 0x400
	v_mul_f32_e32 v44, 0x3db504f3, v44
	s_waitcnt vmcnt(1)
	ds_write_b128 v40, v[24:27] offset:17408
	s_waitcnt vmcnt(0)
	ds_write_b128 v40, v[28:31] offset:17536
	v_mov_b32_e32 v46, v0
	v_mov_b32_e32 v47, v2
	v_mov_b32_e32 v2, v1
	v_mov_b32_e32 v0, v4
	v_mov_b32_e32 v1, v6
	v_mov_b32_e32 v6, v5
	v_mov_b32_e32 v4, v12
	v_mov_b32_e32 v5, v14
	v_mov_b32_e32 v14, v13
	v_mov_b32_e32 v13, v10
	v_mov_b32_e32 v10, v9
	v_lshlrev_b32_e32 v48, 16, v20
	v_and_b32_e32 v49, 0xffff0000, v20
	v_lshlrev_b32_e32 v20, 16, v21
	v_and_b32_e32 v21, 0xffff0000, v21
	v_lshlrev_b32_e32 v52, 16, v22
	v_and_b32_e32 v53, 0xffff0000, v22
	v_lshlrev_b32_e32 v22, 16, v23
	v_and_b32_e32 v23, 0xffff0000, v23
	v_mov_b32_e32 v12, v8
	v_lshlrev_b32_e32 v8, 16, v16
	v_and_b32_e32 v9, 0xffff0000, v16
	v_lshlrev_b32_e32 v16, 16, v17
	v_and_b32_e32 v17, 0xffff0000, v17
	v_lshlrev_b32_e32 v50, 16, v18
	v_and_b32_e32 v51, 0xffff0000, v18
	v_lshlrev_b32_e32 v18, 16, v19
	v_and_b32_e32 v19, 0xffff0000, v19
	v_pk_mul_f32 v[24:25], v[2:3], v[48:49]
	v_pk_mul_f32 v[26:27], v[46:47], v[48:49]
	v_pk_mul_f32 v[28:29], v[6:7], v[20:21]
	v_pk_mul_f32 v[30:31], v[14:15], v[52:53]
	v_pk_mul_f32 v[48:49], v[4:5], v[52:53]
	v_pk_mul_f32 v[52:53], v[10:11], v[22:23]
	v_pk_mul_f32 v[20:21], v[0:1], v[20:21]
	v_pk_mul_f32 v[22:23], v[12:13], v[22:23]
	v_pk_fma_f32 v[24:25], v[46:47], v[8:9], v[24:25] neg_lo:[0,0,1] neg_hi:[0,0,1]
	v_pk_fma_f32 v[2:3], v[2:3], v[8:9], v[26:27]
	v_pk_fma_f32 v[0:1], v[0:1], v[16:17], v[28:29] neg_lo:[0,0,1] neg_hi:[0,0,1]
	v_pk_fma_f32 v[4:5], v[4:5], v[50:51], v[30:31] neg_lo:[0,0,1] neg_hi:[0,0,1]
	v_pk_fma_f32 v[12:13], v[12:13], v[18:19], v[52:53] neg_lo:[0,0,1] neg_hi:[0,0,1]
	v_pk_fma_f32 v[6:7], v[6:7], v[16:17], v[20:21]
	v_pk_fma_f32 v[8:9], v[14:15], v[50:51], v[48:49]
	v_pk_fma_f32 v[10:11], v[10:11], v[18:19], v[22:23]
	v_pk_mul_f32 v[14:15], v[44:45], v[24:25] op_sel_hi:[0,1]
	v_pk_mul_f32 v[2:3], v[44:45], v[2:3] op_sel_hi:[0,1]
	v_pk_mul_f32 v[16:17], v[44:45], v[0:1] op_sel_hi:[0,1]
	v_pk_mul_f32 v[18:19], v[44:45], v[4:5] op_sel_hi:[0,1]
	v_pk_mul_f32 v[12:13], v[44:45], v[12:13] op_sel_hi:[0,1]
	v_pk_mul_f32 v[6:7], v[44:45], v[6:7] op_sel_hi:[0,1]
	v_pk_mul_f32 v[8:9], v[44:45], v[8:9] op_sel_hi:[0,1]
	v_pk_mul_f32 v[10:11], v[44:45], v[10:11] op_sel_hi:[0,1]
	v_cvt_pk_bf16_f32 v0, v14, v15
	v_cvt_pk_bf16_f32 v4, v2, v3
	v_cvt_pk_bf16_f32 v1, v16, v17
	v_cvt_pk_bf16_f32 v2, v18, v19
	v_cvt_pk_bf16_f32 v3, v12, v13
	v_cvt_pk_bf16_f32 v5, v6, v7
	v_cvt_pk_bf16_f32 v6, v8, v9
	v_cvt_pk_bf16_f32 v7, v10, v11
	ds_write_b128 v40, v[0:3]
	ds_write_b128 v40, v[4:7] offset:128
	s_waitcnt vmcnt(0) lgkmcnt(0)
	s_barrier
	ds_read_u16 v0, v41 offset:17408
	ds_read_u16 v1, v41 offset:17680
	ds_read_u16 v2, v41 offset:17952
	ds_read_u16 v3, v41 offset:18224
	ds_read_u16 v4, v41 offset:18496
	ds_read_u16 v5, v41 offset:18768
	ds_read_u16 v6, v41 offset:19040
	ds_read_u16 v7, v41 offset:19312
	ds_read_u16 v8, v42
	ds_read_u16 v9, v42 offset:272
	ds_read_u16 v10, v42 offset:544
	ds_read_u16 v11, v42 offset:816
	ds_read_u16 v12, v42 offset:1088
	ds_read_u16 v13, v42 offset:1360
	ds_read_u16 v14, v42 offset:1632
	ds_read_u16 v15, v42 offset:1904
	ds_read_u16 v20, v43
	ds_read_u16 v21, v43 offset:272
	ds_read_u16 v22, v43 offset:544
	ds_read_u16 v23, v43 offset:816
	ds_read_u16 v24, v43 offset:1088
	ds_read_u16 v25, v43 offset:1360
	ds_read_u16 v26, v43 offset:1632
	ds_read_u16 v27, v43 offset:1904
	ds_read_u16 v28, v41 offset:21760
	ds_read_u16 v29, v41 offset:22032
	ds_read_u16 v45, v41 offset:22304
	ds_read_u16 v46, v41 offset:22576
	ds_read_u16 v47, v41 offset:22848
	ds_read_u16 v48, v41 offset:23120
	ds_read_u16 v49, v41 offset:23392
	ds_read_u16 v50, v41 offset:23664
	ds_read_u16 v51, v42 offset:4352
	ds_read_u16 v52, v42 offset:4624
	ds_read_u16 v53, v42 offset:4896
	ds_read_u16 v54, v42 offset:5168
	ds_read_u16 v55, v42 offset:5440
	ds_read_u16 v56, v42 offset:5712
	ds_read_u16 v57, v42 offset:5984
	ds_read_u16 v58, v42 offset:6256
	ds_read_u16 v59, v43 offset:4352
	ds_read_u16 v60, v43 offset:4624
	ds_read_u16 v61, v43 offset:4896
	ds_read_u16 v62, v43 offset:5168
	ds_read_u16 v63, v43 offset:5440
	ds_read_u16 v64, v43 offset:5712
	ds_read_u16 v65, v43 offset:5984
	ds_read_u16 v66, v43 offset:6256
	ds_read_u16 v67, v41 offset:26112
	ds_read_u16 v68, v41 offset:26384
	ds_read_u16 v69, v41 offset:26656
	ds_read_u16 v70, v41 offset:26928
	ds_read_u16 v71, v41 offset:27200
	ds_read_u16 v72, v41 offset:27472
	ds_read_u16 v73, v41 offset:27744
	ds_read_u16 v74, v41 offset:28016
	ds_read_u16 v75, v42 offset:8704
	ds_read_u16 v76, v42 offset:8976
	ds_read_u16 v77, v42 offset:9248
	ds_read_u16 v78, v42 offset:9520
	ds_read_u16 v79, v42 offset:9792
	ds_read_u16 v80, v42 offset:10064
	ds_read_u16 v81, v42 offset:10336
	ds_read_u16 v82, v42 offset:10608
	ds_read_u16 v83, v43 offset:8704
	ds_read_u16 v84, v43 offset:8976
	ds_read_u16 v85, v43 offset:9248
	ds_read_u16 v86, v43 offset:9520
	ds_read_u16 v87, v43 offset:9792
	ds_read_u16 v88, v43 offset:10064
	ds_read_u16 v89, v43 offset:10336
	ds_read_u16 v90, v43 offset:10608
	ds_read_u16 v91, v41 offset:30464
	ds_read_u16 v92, v41 offset:30736
	ds_read_u16 v93, v41 offset:31008
	ds_read_u16 v94, v41 offset:31280
	ds_read_u16 v95, v41 offset:31552
	ds_read_u16 v96, v41 offset:31824
	ds_read_u16 v97, v41 offset:32096
	ds_read_u16 v98, v41 offset:32368
	ds_read_u16 v99, v42 offset:13056
	ds_read_u16 v100, v42 offset:13328
	ds_read_u16 v101, v42 offset:13600
	ds_read_u16 v102, v42 offset:13872
	ds_read_u16 v103, v42 offset:14144
	ds_read_u16 v104, v42 offset:14416
	ds_read_u16 v105, v42 offset:14688
	ds_read_u16 v106, v42 offset:14960
	s_waitcnt lgkmcnt(14)
	v_lshl_or_b32 v16, v1, 16, v0
	v_lshl_or_b32 v17, v3, 16, v2
	v_lshl_or_b32 v18, v5, 16, v4
	v_lshl_or_b32 v19, v7, 16, v6
	v_lshl_or_b32 v0, v9, 16, v8
	v_lshl_or_b32 v1, v11, 16, v10
	v_lshl_or_b32 v2, v13, 16, v12
	v_lshl_or_b32 v3, v15, 16, v14
	v_lshl_or_b32 v44, v29, 16, v28
	v_lshl_or_b32 v45, v46, 16, v45
	v_mfma_f32_32x32x16_bf16 v[0:15], v[16:19], v[0:3], 0
	v_lshl_or_b32 v46, v48, 16, v47
	v_lshl_or_b32 v47, v50, 16, v49
	v_lshl_or_b32 v20, v21, 16, v20
	v_lshl_or_b32 v21, v23, 16, v22
	v_lshl_or_b32 v22, v25, 16, v24
	v_lshl_or_b32 v23, v27, 16, v26
	v_lshl_or_b32 v48, v52, 16, v51
	v_lshl_or_b32 v49, v54, 16, v53
	v_mfma_f32_32x32x16_bf16 v[16:31], v[16:19], v[20:23], 0
	v_lshl_or_b32 v50, v56, 16, v55
	v_lshl_or_b32 v51, v58, 16, v57
	v_lshl_or_b32 v52, v68, 16, v67
	v_lshl_or_b32 v53, v70, 16, v69
	v_lshl_or_b32 v54, v72, 16, v71
	v_lshl_or_b32 v55, v74, 16, v73
	ds_read_u16 v107, v43 offset:13056
	ds_read_u16 v108, v43 offset:13328
	v_mfma_f32_32x32x16_bf16 v[0:15], v[44:47], v[48:51], v[0:15]
	v_lshl_or_b32 v48, v60, 16, v59
	v_lshl_or_b32 v49, v62, 16, v61
	v_lshl_or_b32 v50, v64, 16, v63
	v_lshl_or_b32 v51, v66, 16, v65
	ds_read_u16 v56, v43 offset:13600
	ds_read_u16 v57, v43 offset:13872
	ds_read_u16 v58, v43 offset:14144
	ds_read_u16 v59, v43 offset:14416
	v_mfma_f32_32x32x16_bf16 v[16:31], v[44:47], v[48:51], v[16:31]
	v_lshl_or_b32 v44, v76, 16, v75
	v_lshl_or_b32 v45, v78, 16, v77
	v_lshl_or_b32 v46, v80, 16, v79
	v_lshl_or_b32 v47, v82, 16, v81
	v_lshl_or_b32 v48, v92, 16, v91
	s_waitcnt lgkmcnt(14)
	v_lshl_or_b32 v49, v94, 16, v93
	v_lshl_or_b32 v50, v96, 16, v95
	v_mfma_f32_32x32x16_bf16 v[0:15], v[52:55], v[44:47], v[0:15]
	v_lshl_or_b32 v51, v98, 16, v97
	v_lshl_or_b32 v44, v84, 16, v83
	v_lshl_or_b32 v45, v86, 16, v85
	v_lshl_or_b32 v46, v88, 16, v87
	v_lshl_or_b32 v47, v90, 16, v89
	s_nop 1
	v_mfma_f32_32x32x16_bf16 v[16:31], v[52:55], v[44:47], v[16:31]
	s_waitcnt lgkmcnt(12)
	v_lshl_or_b32 v44, v100, 16, v99
	s_waitcnt lgkmcnt(10)
	v_lshl_or_b32 v45, v102, 16, v101
	s_waitcnt lgkmcnt(8)
	v_lshl_or_b32 v46, v104, 16, v103
	s_waitcnt lgkmcnt(6)
	v_lshl_or_b32 v47, v106, 16, v105
	s_nop 1
	v_mfma_f32_32x32x16_bf16 v[0:15], v[48:51], v[44:47], v[0:15]
	ds_read_u16 v47, v43 offset:14688
	ds_read_u16 v52, v43 offset:14960
	s_waitcnt lgkmcnt(6)
	v_lshl_or_b32 v44, v108, 16, v107
	s_waitcnt lgkmcnt(4)
	v_lshl_or_b32 v45, v57, 16, v56
	s_waitcnt lgkmcnt(2)
	v_lshl_or_b32 v46, v59, 16, v58
	s_waitcnt lgkmcnt(0)
	v_lshl_or_b32 v47, v52, 16, v47
	s_nop 1
	v_cvt_pk_bf16_f32 v0, v0, s0
	v_mfma_f32_32x32x16_bf16 v[16:31], v[48:51], v[44:47], v[16:31]
	v_cvt_pk_bf16_f32 v1, v1, s0
	v_cvt_pk_bf16_f32 v2, v2, s0
	v_cvt_pk_bf16_f32 v3, v3, s0
	v_cvt_pk_bf16_f32 v4, v4, s0
	v_cvt_pk_bf16_f32 v5, v5, s0
	v_cvt_pk_bf16_f32 v6, v6, s0
	v_cvt_pk_bf16_f32 v7, v7, s0
	s_nop 4
	v_cvt_pk_bf16_f32 v16, v16, s0
	v_cvt_pk_bf16_f32 v17, v17, s0
	v_cvt_pk_bf16_f32 v18, v18, s0
	v_cvt_pk_bf16_f32 v19, v19, s0
	v_cvt_pk_bf16_f32 v20, v20, s0
	v_cvt_pk_bf16_f32 v21, v21, s0
	v_cvt_pk_bf16_f32 v22, v22, s0
	v_cvt_pk_bf16_f32 v23, v23, s0
	v_cvt_pk_bf16_f32 v8, v8, s0
	v_cvt_pk_bf16_f32 v24, v24, s0
	v_cvt_pk_bf16_f32 v9, v9, s0
	v_cvt_pk_bf16_f32 v25, v25, s0
	v_cvt_pk_bf16_f32 v10, v10, s0
	v_cvt_pk_bf16_f32 v26, v26, s0
	v_cvt_pk_bf16_f32 v11, v11, s0
	v_cvt_pk_bf16_f32 v27, v27, s0
	v_cvt_pk_bf16_f32 v12, v12, s0
	v_cvt_pk_bf16_f32 v28, v28, s0
	v_cvt_pk_bf16_f32 v13, v13, s0
	v_cvt_pk_bf16_f32 v29, v29, s0
	v_cvt_pk_bf16_f32 v14, v14, s0
	v_cvt_pk_bf16_f32 v30, v30, s0
	v_cvt_pk_bf16_f32 v15, v15, s0
	v_cvt_pk_bf16_f32 v31, v31, s0
	global_store_short v[36:37], v0, off offset:-2880
	global_store_short v[36:37], v16, off offset:-2816
	global_store_short v[36:37], v1, off offset:-2624
	global_store_short v[36:37], v17, off offset:-2560
	global_store_short v[36:37], v2, off offset:-2368
	global_store_short v[36:37], v18, off offset:-2304
	global_store_short v[36:37], v3, off offset:-2112
	global_store_short v[36:37], v19, off offset:-2048
	global_store_short v[36:37], v4, off offset:-832
	global_store_short v[36:37], v20, off offset:-768
	global_store_short v[36:37], v5, off offset:-576
	global_store_short v[36:37], v21, off offset:-512
	global_store_short v[36:37], v6, off offset:-320
	global_store_short v[36:37], v22, off offset:-256
	global_store_short v[36:37], v7, off offset:-64
	global_store_short v[34:35], v23, off offset:-4096
	global_store_short v[34:35], v8, off offset:-2880
	global_store_short v[34:35], v24, off offset:-2816
	global_store_short v[34:35], v9, off offset:-2624
	global_store_short v[34:35], v25, off offset:-2560
	global_store_short v[34:35], v10, off offset:-2368
	global_store_short v[34:35], v26, off offset:-2304
	global_store_short v[34:35], v11, off offset:-2112
	global_store_short v[34:35], v27, off offset:-2048
	global_store_short v[34:35], v12, off offset:-832
	global_store_short v[34:35], v28, off offset:-768
	global_store_short v[34:35], v13, off offset:-576
	global_store_short v[34:35], v29, off offset:-512
	global_store_short v[34:35], v14, off offset:-320
	global_store_short v[34:35], v30, off offset:-256
	global_store_short v[34:35], v15, off offset:-64
	global_store_short v[34:35], v31, off
	s_waitcnt lgkmcnt(0)
	s_barrier
	v_lshl_add_u64 v[34:35], v[34:35], 0, s[34:35]
	s_cbranch_scc1 .LBB0_464

.LBB0_580:
	s_or_b64 exec, exec, s[4:5]
	v_add_u32_e32 v0, s7, v93
	v_mov_b64_e32 v[2:3], s[12:13]
	v_mad_i64_i32 v[2:3], s[4:5], v0, s85, v[2:3]
	s_lshl_b32 s26, s16, 1
	v_lshl_add_u64 v[2:3], v[2:3], 0, s[26:27]
	v_mov_b32_e32 v87, v169
	v_lshl_add_u64 v[24:25], v[2:3], 0, v[86:87]
	v_add_co_u32_e64 v2, s[4:5], s86, v24
	s_waitcnt vmcnt(0) lgkmcnt(0)
	s_barrier
	s_nop 0
	v_addc_co_u32_e64 v3, s[4:5], 0, v25, s[4:5]
	global_load_dwordx2 v[20:21], v[2:3], off offset:2048
	s_waitcnt lgkmcnt(0)
	v_ashrrev_i32_e32 v1, 31, v0
	v_lshlrev_b64 v[0:1], 11, v[0:1]
	v_lshl_add_u64 v[0:1], s[10:11], 0, v[0:1]
	v_lshl_add_u64 v[28:29], v[0:1], 0, s[26:27]
	s_lshl_b32 s26, s16, 2
	v_lshl_add_u64 v[8:9], v[82:83], 0, s[26:27]
	global_load_dwordx4 v[0:3], v[8:9], off
	v_add_u32_e32 v22, s14, v88
	ds_read2st64_b32 v[22:23], v22 offset0:204 offset1:205
	ds_read_b32 v34, v96 offset:52224
	ds_read_b32 v35, v97 offset:52224
	s_mov_b64 s[4:5], 0x1800
	v_lshl_add_u64 v[26:27], v[24:25], 0, s[4:5]
	v_lshl_add_u64 v[24:25], v[28:29], 0, v[86:87]
	global_load_dwordx2 v[30:31], v[26:27], off offset:16
	global_load_dwordx2 v[28:29], v[26:27], off offset:48
	s_waitcnt lgkmcnt(0)
	v_pk_add_f32 v[22:23], v[22:23], v[34:35]
	s_mov_b32 s7, 0xf700000
	v_add_f32_e32 v22, v22, v23
	v_fmamk_f32 v22, v22, 0x3c000000, v226
	v_rsq_f32_e32 v22, v22
	v_add_co_u32_e64 v34, s[4:5], s7, v24
	s_add_i32 s6, s6, s24
	v_pk_mul_f32 v[32:33], v[32:33], v[22:23] op_sel_hi:[1,0]
	v_pk_mul_f32 v[18:19], v[18:19], v[22:23] op_sel_hi:[1,0]
	v_addc_co_u32_e64 v35, s[4:5], 0, v25, s[4:5]
	s_mov_b64 s[4:5], 0xf700400
	s_add_i32 s15, s15, s76
	s_cmpk_gt_i32 s6, 0x3ff
	v_lshl_add_u64 v[84:85], v[84:85], 0, s[34:35]
	s_waitcnt vmcnt(3)
	v_lshlrev_b32_e32 v36, 16, v20
	v_and_b32_e32 v37, 0xffff0000, v20
	v_lshlrev_b32_e32 v20, 16, v21
	v_and_b32_e32 v21, 0xffff0000, v21
	v_mul_f32_e32 v23, 0xbfb8aa3b, v36
	v_mul_f32_e32 v38, 0xbfb8aa3b, v37
	v_mul_f32_e32 v39, 0xbfb8aa3b, v20
	v_mul_f32_e32 v40, 0xbfb8aa3b, v21
	v_exp_f32_e32 v23, v23
	v_exp_f32_e32 v38, v38
	v_exp_f32_e32 v39, v39
	v_exp_f32_e32 v40, v40
	v_add_f32_e32 v23, 1.0, v23
	v_add_f32_e32 v41, 1.0, v38
	v_add_f32_e32 v42, 1.0, v39
	v_add_f32_e32 v43, 1.0, v40
	v_rcp_f32_e32 v38, v23
	v_rcp_f32_e32 v39, v41
	v_rcp_f32_e32 v40, v42
	v_rcp_f32_e32 v41, v43
	s_waitcnt vmcnt(2)
	v_pk_mul_f32 v[0:1], v[0:1], v[32:33]
	v_pk_mul_f32 v[2:3], v[2:3], v[18:19]
	v_pk_mul_f32 v[18:19], v[38:39], v[36:37]
	v_pk_mul_f32 v[20:21], v[40:41], v[20:21]
	v_pk_mul_f32 v[0:1], v[0:1], v[18:19]
	v_pk_mul_f32 v[2:3], v[2:3], v[20:21]
	v_cvt_pk_bf16_f32 v0, v0, v1
	v_cvt_pk_bf16_f32 v1, v2, v3
	global_store_dwordx2 v[34:35], v[0:1], off offset:1024
	global_load_dwordx4 v[18:21], v[8:9], off offset:32
	global_load_dwordx2 v[2:3], v[26:27], off offset:32
	v_lshl_add_u64 v[0:1], v[24:25], 0, s[4:5]
	s_waitcnt vmcnt(4)
	v_lshlrev_b32_e32 v24, 16, v30
	v_and_b32_e32 v25, 0xffff0000, v30
	v_lshlrev_b32_e32 v26, 16, v31
	v_and_b32_e32 v27, 0xffff0000, v31
	v_mul_f32_e32 v23, 0xbfb8aa3b, v24
	v_mul_f32_e32 v30, 0xbfb8aa3b, v25
	v_mul_f32_e32 v31, 0xbfb8aa3b, v26
	v_mul_f32_e32 v32, 0xbfb8aa3b, v27
	v_exp_f32_e32 v23, v23
	v_exp_f32_e32 v30, v30
	v_exp_f32_e32 v31, v31
	v_exp_f32_e32 v32, v32
	v_add_f32_e32 v23, 1.0, v23
	v_add_f32_e32 v33, 1.0, v30
	v_add_f32_e32 v34, 1.0, v31
	v_add_f32_e32 v35, 1.0, v32
	v_rcp_f32_e32 v30, v23
	v_rcp_f32_e32 v31, v33
	v_rcp_f32_e32 v32, v34
	v_rcp_f32_e32 v33, v35
	v_pk_mul_f32 v[14:15], v[14:15], v[22:23] op_sel_hi:[1,0]
	v_pk_mul_f32 v[16:17], v[16:17], v[22:23] op_sel_hi:[1,0]
	v_pk_mul_f32 v[24:25], v[30:31], v[24:25]
	v_pk_mul_f32 v[26:27], v[32:33], v[26:27]
	s_waitcnt vmcnt(1)
	v_pk_mul_f32 v[14:15], v[14:15], v[18:19]
	v_pk_mul_f32 v[16:17], v[16:17], v[20:21]
	v_pk_mul_f32 v[14:15], v[14:15], v[24:25]
	v_pk_mul_f32 v[16:17], v[16:17], v[26:27]
	v_cvt_pk_bf16_f32 v14, v14, v15
	v_cvt_pk_bf16_f32 v15, v16, v17
	global_store_dwordx2 v[0:1], v[14:15], off offset:16
	global_load_dwordx4 v[14:17], v[8:9], off offset:64
	s_waitcnt vmcnt(2)
	v_lshlrev_b32_e32 v18, 16, v2
	v_and_b32_e32 v19, 0xffff0000, v2
	v_lshlrev_b32_e32 v2, 16, v3
	v_and_b32_e32 v3, 0xffff0000, v3
	v_mul_f32_e32 v20, 0xbfb8aa3b, v18
	v_mul_f32_e32 v21, 0xbfb8aa3b, v19
	v_mul_f32_e32 v23, 0xbfb8aa3b, v2
	v_mul_f32_e32 v24, 0xbfb8aa3b, v3
	v_exp_f32_e32 v20, v20
	v_exp_f32_e32 v21, v21
	v_exp_f32_e32 v23, v23
	v_exp_f32_e32 v24, v24
	v_add_f32_e32 v20, 1.0, v20
	v_add_f32_e32 v21, 1.0, v21
	v_add_f32_e32 v23, 1.0, v23
	v_add_f32_e32 v25, 1.0, v24
	v_rcp_f32_e32 v20, v20
	v_rcp_f32_e32 v21, v21
	v_rcp_f32_e32 v24, v23
	v_rcp_f32_e32 v25, v25
	v_pk_mul_f32 v[10:11], v[10:11], v[22:23] op_sel_hi:[1,0]
	v_pk_mul_f32 v[12:13], v[12:13], v[22:23] op_sel_hi:[1,0]
	v_pk_mul_f32 v[18:19], v[20:21], v[18:19]
	v_pk_mul_f32 v[2:3], v[24:25], v[2:3]
	v_pk_mul_f32 v[4:5], v[4:5], v[22:23] op_sel_hi:[1,0]
	v_pk_mul_f32 v[6:7], v[6:7], v[22:23] op_sel_hi:[1,0]
	s_waitcnt vmcnt(0)
	v_pk_mul_f32 v[10:11], v[10:11], v[14:15]
	v_pk_mul_f32 v[12:13], v[12:13], v[16:17]
	v_pk_mul_f32 v[10:11], v[10:11], v[18:19]
	v_pk_mul_f32 v[2:3], v[12:13], v[2:3]
	v_cvt_pk_bf16_f32 v10, v10, v11
	v_cvt_pk_bf16_f32 v11, v2, v3
	global_store_dwordx2 v[0:1], v[10:11], off offset:32
	global_load_dwordx4 v[8:11], v[8:9], off offset:96
	v_lshlrev_b32_e32 v2, 16, v28
	v_and_b32_e32 v3, 0xffff0000, v28
	v_lshlrev_b32_e32 v12, 16, v29
	v_and_b32_e32 v13, 0xffff0000, v29
	v_mul_f32_e32 v14, 0xbfb8aa3b, v2
	v_mul_f32_e32 v15, 0xbfb8aa3b, v3
	v_mul_f32_e32 v16, 0xbfb8aa3b, v12
	v_mul_f32_e32 v17, 0xbfb8aa3b, v13
	v_exp_f32_e32 v14, v14
	v_exp_f32_e32 v15, v15
	v_exp_f32_e32 v16, v16
	v_exp_f32_e32 v17, v17
	v_add_f32_e32 v14, 1.0, v14
	v_add_f32_e32 v15, 1.0, v15
	v_add_f32_e32 v16, 1.0, v16
	v_add_f32_e32 v17, 1.0, v17
	v_rcp_f32_e32 v14, v14
	v_rcp_f32_e32 v15, v15
	v_rcp_f32_e32 v16, v16
	v_rcp_f32_e32 v17, v17
	v_pk_mul_f32 v[2:3], v[14:15], v[2:3]
	v_pk_mul_f32 v[12:13], v[16:17], v[12:13]
	s_waitcnt vmcnt(0)
	v_pk_mul_f32 v[4:5], v[4:5], v[8:9]
	v_pk_mul_f32 v[6:7], v[6:7], v[10:11]
	v_pk_mul_f32 v[2:3], v[4:5], v[2:3]
	v_pk_mul_f32 v[4:5], v[6:7], v[12:13]
	v_cvt_pk_bf16_f32 v2, v2, v3
	v_cvt_pk_bf16_f32 v3, v4, v5
	global_store_dwordx2 v[0:1], v[2:3], off offset:48
	s_waitcnt lgkmcnt(0)
	s_barrier
	s_cbranch_scc1 .LBB0_583
